# GEMM main loop: all 16 LDS-DMA loads per 2 K-steps in scalar-base + lane-offset form (no 64-bit VALU address adds left in the loop)
# speedup vs baseline: 1.0101x; 1.0036x over previous
; #define PG8_STAGE(bufoff, gbase, voff) do { _Pragma("unroll") for (int _i = 0; _i < 2; ++_i) \
;         __builtin_amdgcn_global_load_lds((const unsigned*)((const char*)(gbase) + (voff)[_i]), (LAS unsigned*)(lds + (bufoff) + ldsw + _i * 8192), 16, 0, 0); } while (0)
; #define PG8_LDA(dst, b, h) do { _Pragma("unroll") for (int m = 0; m < 4; ++m) _Pragma("unroll") for (int k = 0; k < 2; ++k) dst[m][k] = *(const LAS h16x8*)(lds + PG8_SA(b, h) + aoff + m * 2048 + k * 1024); } while (0)
; #define PG8_LDB(dst, b, h) do { _Pragma("unroll") for (int n = 0; n < 2; ++n) _Pragma("unroll") for (int k = 0; k < 2; ++k) dst[n][k] = *(const LAS h16x8*)(lds + PG8_SB(b, h) + boff + n * 2048 + k * 1024); } while (0)
; #define PG8_MMA(ai, bj, At, Bt) do { __builtin_amdgcn_s_setprio(1); _Pragma("unroll") for (int m = 0; m < 4; ++m) _Pragma("unroll") for (int n = 0; n < 2; ++n) _Pragma("unroll") for (int k = 0; k < 2; ++k) \
;         acc[ai][bj][m][n] = __builtin_amdgcn_mfma_f32_16x16x32_f16(Bt[n][k], At[m][k], acc[ai][bj][m][n], 0, 0, 0); __builtin_amdgcn_s_setprio(0); } while (0)
; #define PG8_WAIT_V(n) asm volatile("s_waitcnt vmcnt(" #n ")" ::: "memory")
; #define PG8_WAIT_L(n) asm volatile("s_waitcnt lgkmcnt(" #n ")" ::: "memory")
; #define PG8_BAR __builtin_amdgcn_s_barrier()
; #define PG8_SCHED __builtin_amdgcn_sched_barrier(0)
; __device__ __forceinline__ void gemm_phase(LAS unsigned char* lds, const Gemm g, const StaticOrder& S, const Epi& E) {
;     ...
;             const char* a1 = cA + PG8_KOFF(t + 1);
;             const char* a2 = last ? nA : cA + PG8_KOFF(t + 2); const char* b2 = last ? nB : cB + (size_t)(t + 2) * kstep;
;             const char* a3 = a2 + kstep; const char* b3 = b2 + kstep;
;             PG8_LDB(B0, 0, 0); PG8_SCHED; PG8_LDA(At, 0, 0); PG8_STAGE(PG8_SA(1, 1), a1 + hstepA, voffA);
;             PG8_WAIT_L(8); PG8_BAR; PG8_WAIT_L(0); PG8_MMA(0, 0, At, B0); PG8_BAR; PG8_SCHED;
;             PG8_LDB(B1, 0, 1); PG8_STAGE(PG8_SB(0, 0), b2, voffB);
;             PG8_BAR; PG8_WAIT_L(0); PG8_MMA(0, 1, At, B1); PG8_BAR;
;             PG8_LDA(At, 0, 1); PG8_STAGE(PG8_SA(0, 0), a2, voffA);
;             PG8_BAR; PG8_WAIT_L(0); PG8_MMA(1, 0, At, B0); PG8_BAR; PG8_SCHED;
;             PG8_STAGE(PG8_SB(0, 1), b2 + hstepB, voffB);
;             PG8_WAIT_V(6); PG8_BAR; PG8_MMA(1, 1, At, B1); PG8_BAR;
.Lprio_skip:
.LBB0_762:
	s_cmp_gt_u32 s34, 15
	s_cselect_b64 s[36:37], -1, 0
	s_and_b64 s[36:37], s[6:7], s[36:37]
	s_and_b64 s[36:37], s[36:37], exec
	s_cselect_b32 s42, 0xfffff000, 0
	s_cselect_b32 s43, -1, 0
	s_add_i32 s38, s34, 2
	s_cmp_gt_u32 s34, 13
	s_cselect_b64 s[36:37], -1, 0
	s_and_b64 s[36:37], s[6:7], s[36:37]
	s_and_b64 s[36:37], s[36:37], exec
	s_cselect_b32 s36, 0xfffff000, 0
	s_cselect_b32 s35, -1, 0
	s_add_u32 s36, s0, s36
	s_addc_u32 s35, s1, s35
	s_add_u32 s36, s36, 0x80
	s_addc_u32 s35, s35, 0
	s_add_i32 s39, 0, 0x10000
	v_add_u32_e32 v140, s39, v238
	ds_read_b128 v[128:131], v140
	ds_read_b128 v[132:135], v140 offset:1024
	ds_read_b128 v[136:139], v140 offset:2048
	ds_read_b128 v[140:143], v140 offset:3072
	s_cmp_eq_u32 s66, s34
	s_cselect_b32 s34, s4, s36
	s_cselect_b32 s35, s5, s35
	s_cselect_b32 s37, s29, s33
	s_cselect_b32 s36, s28, s27
	s_add_u32 s86, s0, s42
	s_addc_u32 s87, s1, s43
	s_add_i32 m0, s58, 0xc000
	ds_read_b128 v[144:147], v239
	ds_read_b128 v[148:151], v239 offset:1024
	ds_read_b128 v[152:155], v239 offset:2048
	ds_read_b128 v[156:159], v239 offset:3072
	ds_read_b128 v[160:163], v239 offset:4096
	ds_read_b128 v[164:167], v239 offset:5120
	ds_read_b128 v[168:171], v239 offset:6144
	ds_read_b128 v[172:175], v239 offset:7168
	global_load_lds_dwordx4 v212, s[86:87]
	s_add_i32 m0, s58, 0xe000
	s_nop 0
	global_load_lds_dwordx4 v214, s[86:87]
	s_waitcnt lgkmcnt(8)
	s_barrier
	s_waitcnt lgkmcnt(0)
	s_waitcnt lgkmcnt(0)
	v_mfma_f32_16x16x32_f16 v[124:127], v[128:131], v[144:147], v[124:127]
	v_mfma_f32_16x16x32_f16 v[120:123], v[136:139], v[144:147], v[120:123]
	v_mfma_f32_16x16x32_f16 v[108:111], v[128:131], v[152:155], v[108:111]
	v_mfma_f32_16x16x32_f16 v[104:107], v[136:139], v[152:155], v[104:107]
	v_mfma_f32_16x16x32_f16 v[92:95], v[128:131], v[160:163], v[92:95]
	v_mfma_f32_16x16x32_f16 v[88:91], v[136:139], v[160:163], v[88:91]
	v_mfma_f32_16x16x32_f16 v[76:79], v[128:131], v[168:171], v[76:79]
	v_mfma_f32_16x16x32_f16 v[72:75], v[136:139], v[168:171], v[72:75]
	v_mfma_f32_16x16x32_f16 v[124:127], v[132:135], v[148:151], v[124:127]
	v_mfma_f32_16x16x32_f16 v[120:123], v[140:143], v[148:151], v[120:123]
	v_mfma_f32_16x16x32_f16 v[108:111], v[132:135], v[156:159], v[108:111]
	v_mfma_f32_16x16x32_f16 v[104:107], v[140:143], v[156:159], v[104:107]
	v_mfma_f32_16x16x32_f16 v[92:95], v[132:135], v[164:167], v[92:95]
	v_mfma_f32_16x16x32_f16 v[88:91], v[140:143], v[164:167], v[88:91]
	v_mfma_f32_16x16x32_f16 v[76:79], v[132:135], v[172:175], v[76:79]
	v_mfma_f32_16x16x32_f16 v[72:75], v[140:143], v[172:175], v[72:75]
	s_barrier
	s_add_i32 s42, 0, 0x14000
	s_add_i32 s39, s39, s31
	v_add_u32_e32 v188, s42, v238
	s_add_u32 s86, s36, 0x80
	s_addc_u32 s87, s37, 0
	s_mov_b32 m0, s39
	ds_read_b128 v[176:179], v188
	ds_read_b128 v[180:183], v188 offset:1024
	ds_read_b128 v[184:187], v188 offset:2048
	ds_read_b128 v[188:191], v188 offset:3072
	global_load_lds_dwordx4 v206, s[36:37]
	s_add_i32 m0, s39, 0x2000
	s_nop 0
	global_load_lds_dwordx4 v210, s[36:37]
	s_barrier
	s_waitcnt lgkmcnt(0)
	s_waitcnt lgkmcnt(0)
	v_mfma_f32_16x16x32_f16 v[116:119], v[176:179], v[144:147], v[116:119]
	v_mfma_f32_16x16x32_f16 v[112:115], v[184:187], v[144:147], v[112:115]
	v_mfma_f32_16x16x32_f16 v[100:103], v[176:179], v[152:155], v[100:103]
	v_mfma_f32_16x16x32_f16 v[96:99], v[184:187], v[152:155], v[96:99]
	v_mfma_f32_16x16x32_f16 v[84:87], v[176:179], v[160:163], v[84:87]
	v_mfma_f32_16x16x32_f16 v[80:83], v[184:187], v[160:163], v[80:83]
	v_mfma_f32_16x16x32_f16 v[68:71], v[176:179], v[168:171], v[68:71]
	v_mfma_f32_16x16x32_f16 v[64:67], v[184:187], v[168:171], v[64:67]
	v_mfma_f32_16x16x32_f16 v[116:119], v[180:183], v[148:151], v[116:119]
	v_mfma_f32_16x16x32_f16 v[112:115], v[188:191], v[148:151], v[112:115]
	v_mfma_f32_16x16x32_f16 v[100:103], v[180:183], v[156:159], v[100:103]
	v_mfma_f32_16x16x32_f16 v[96:99], v[188:191], v[156:159], v[96:99]
	v_mfma_f32_16x16x32_f16 v[84:87], v[180:183], v[164:167], v[84:87]
	v_mfma_f32_16x16x32_f16 v[80:83], v[188:191], v[164:167], v[80:83]
	v_mfma_f32_16x16x32_f16 v[68:71], v[180:183], v[172:175], v[68:71]
	v_mfma_f32_16x16x32_f16 v[64:67], v[188:191], v[172:175], v[64:67]
	s_mov_b32 m0, s58
	s_add_u32 s88, s34, 0x80
	s_addc_u32 s89, s35, 0
	s_barrier
	ds_read_b128 v[144:147], v239 offset:16384
	ds_read_b128 v[148:151], v239 offset:17408
	ds_read_b128 v[152:155], v239 offset:18432
	ds_read_b128 v[156:159], v239 offset:19456
	ds_read_b128 v[160:163], v239 offset:20480
	ds_read_b128 v[164:167], v239 offset:21504
	ds_read_b128 v[168:171], v239 offset:22528
	ds_read_b128 v[172:175], v239 offset:23552
	global_load_lds_dwordx4 v204, s[34:35]
	s_mov_b32 m0, s59
	s_nop 0
	global_load_lds_dwordx4 v208, s[34:35]
	s_barrier
	s_waitcnt lgkmcnt(0)
	s_waitcnt lgkmcnt(0)
	v_mfma_f32_16x16x32_f16 v[60:63], v[128:131], v[144:147], v[60:63]
	v_mfma_f32_16x16x32_f16 v[56:59], v[136:139], v[144:147], v[56:59]
	v_mfma_f32_16x16x32_f16 v[44:47], v[128:131], v[152:155], v[44:47]
	v_mfma_f32_16x16x32_f16 v[40:43], v[136:139], v[152:155], v[40:43]
	v_mfma_f32_16x16x32_f16 v[28:31], v[128:131], v[160:163], v[28:31]
	v_mfma_f32_16x16x32_f16 v[24:27], v[136:139], v[160:163], v[24:27]
	v_mfma_f32_16x16x32_f16 v[12:15], v[128:131], v[168:171], v[12:15]
	v_mfma_f32_16x16x32_f16 v[8:11], v[136:139], v[168:171], v[8:11]
	v_mfma_f32_16x16x32_f16 v[60:63], v[132:135], v[148:151], v[60:63]
	v_mfma_f32_16x16x32_f16 v[56:59], v[140:143], v[148:151], v[56:59]
	v_mfma_f32_16x16x32_f16 v[44:47], v[132:135], v[156:159], v[44:47]
	v_mfma_f32_16x16x32_f16 v[40:43], v[140:143], v[156:159], v[40:43]
	v_mfma_f32_16x16x32_f16 v[28:31], v[132:135], v[164:167], v[28:31]
	v_mfma_f32_16x16x32_f16 v[24:27], v[140:143], v[164:167], v[24:27]
	v_mfma_f32_16x16x32_f16 v[12:15], v[132:135], v[172:175], v[12:15]
	v_mfma_f32_16x16x32_f16 v[8:11], v[140:143], v[172:175], v[8:11]
	s_barrier
; #define PG8_STAGE(bufoff, gbase, voff) do { _Pragma("unroll") for (int _i = 0; _i < 2; ++_i) \
;         __builtin_amdgcn_global_load_lds((const unsigned*)((const char*)(gbase) + (voff)[_i]), (LAS unsigned*)(lds + (bufoff) + ldsw + _i * 8192), 16, 0, 0); } while (0)
; #define PG8_LDA(dst, b, h) do { _Pragma("unroll") for (int m = 0; m < 4; ++m) _Pragma("unroll") for (int k = 0; k < 2; ++k) dst[m][k] = *(const LAS h16x8*)(lds + PG8_SA(b, h) + aoff + m * 2048 + k * 1024); } while (0)
; #define PG8_LDB(dst, b, h) do { _Pragma("unroll") for (int n = 0; n < 2; ++n) _Pragma("unroll") for (int k = 0; k < 2; ++k) dst[n][k] = *(const LAS h16x8*)(lds + PG8_SB(b, h) + boff + n * 2048 + k * 1024); } while (0)
; #define PG8_MMA(ai, bj, At, Bt) do { __builtin_amdgcn_s_setprio(1); _Pragma("unroll") for (int m = 0; m < 4; ++m) _Pragma("unroll") for (int n = 0; n < 2; ++n) _Pragma("unroll") for (int k = 0; k < 2; ++k) \
;         acc[ai][bj][m][n] = __builtin_amdgcn_mfma_f32_16x16x32_f16(Bt[n][k], At[m][k], acc[ai][bj][m][n], 0, 0, 0); __builtin_amdgcn_s_setprio(0); } while (0)
; #define PG8_WAIT_V(n) asm volatile("s_waitcnt vmcnt(" #n ")" ::: "memory")
; #define PG8_WAIT_L(n) asm volatile("s_waitcnt lgkmcnt(" #n ")" ::: "memory")
; #define PG8_BAR __builtin_amdgcn_s_barrier()
; #define PG8_SCHED __builtin_amdgcn_sched_barrier(0)
; __device__ __forceinline__ void gemm_phase(LAS unsigned char* lds, const Gemm g, const StaticOrder& S, const Epi& E) {
;     ...
;             PG8_WAIT_V(6); PG8_BAR; PG8_MMA(1, 1, At, B1); PG8_BAR;
;             PG8_LDB(B0, 1, 0); PG8_SCHED; PG8_LDA(At, 1, 0); PG8_STAGE(PG8_SA(0, 1), a2 + hstepA, voffA);
;             PG8_WAIT_L(8); PG8_BAR; PG8_WAIT_L(0); PG8_MMA(0, 0, At, B0); PG8_BAR; PG8_SCHED;
;             PG8_LDB(B1, 1, 1); PG8_STAGE(PG8_SB(1, 0), b3, voffB);
;             PG8_BAR; PG8_WAIT_L(0); PG8_MMA(0, 1, At, B1); PG8_BAR;
;             PG8_LDA(At, 1, 1); PG8_STAGE(PG8_SA(1, 0), a3, voffA);
	s_add_u32 s36, s36, s18
	s_addc_u32 s37, s37, s19
	s_add_i32 s39, s42, s31
	s_add_u32 s96, s36, 0x80
	s_addc_u32 s97, s37, 0
	s_mov_b32 m0, s39
	global_load_lds_dwordx4 v206, s[36:37]
	s_add_i32 m0, s39, 0x2000
	s_nop 0
	global_load_lds_dwordx4 v210, s[36:37]
	s_waitcnt vmcnt(6)
	s_barrier
	v_mfma_f32_16x16x32_f16 v[52:55], v[176:179], v[144:147], v[52:55]
	v_mfma_f32_16x16x32_f16 v[48:51], v[184:187], v[144:147], v[48:51]
	v_mfma_f32_16x16x32_f16 v[36:39], v[176:179], v[152:155], v[36:39]
	v_mfma_f32_16x16x32_f16 v[32:35], v[184:187], v[152:155], v[32:35]
	v_mfma_f32_16x16x32_f16 v[20:23], v[176:179], v[160:163], v[20:23]
	v_mfma_f32_16x16x32_f16 v[16:19], v[184:187], v[160:163], v[16:19]
	v_mfma_f32_16x16x32_f16 v[4:7], v[176:179], v[168:171], v[4:7]
	v_mfma_f32_16x16x32_f16 v[0:3], v[184:187], v[168:171], v[0:3]
	v_mfma_f32_16x16x32_f16 v[52:55], v[180:183], v[148:151], v[52:55]
	v_mfma_f32_16x16x32_f16 v[48:51], v[188:191], v[148:151], v[48:51]
	v_mfma_f32_16x16x32_f16 v[36:39], v[180:183], v[156:159], v[36:39]
	v_mfma_f32_16x16x32_f16 v[32:35], v[188:191], v[156:159], v[32:35]
	v_mfma_f32_16x16x32_f16 v[20:23], v[180:183], v[164:167], v[20:23]
	v_mfma_f32_16x16x32_f16 v[16:19], v[188:191], v[164:167], v[16:19]
	v_mfma_f32_16x16x32_f16 v[4:7], v[180:183], v[172:175], v[4:7]
	v_mfma_f32_16x16x32_f16 v[0:3], v[188:191], v[172:175], v[0:3]
	s_add_i32 s36, 0, 0x18000
	v_add_u32_e32 v140, s36, v238
	s_barrier
	ds_read_b128 v[128:131], v140
	ds_read_b128 v[132:135], v140 offset:1024
	ds_read_b128 v[136:139], v140 offset:2048
	ds_read_b128 v[140:143], v140 offset:3072
	s_add_u32 s34, s34, s16
	s_addc_u32 s35, s35, s17
	s_mov_b32 m0, s60
	ds_read_b128 v[144:147], v239 offset:32768
	ds_read_b128 v[148:151], v239 offset:33792
	ds_read_b128 v[152:155], v239 offset:34816
	ds_read_b128 v[156:159], v239 offset:35840
	ds_read_b128 v[160:163], v239 offset:36864
	ds_read_b128 v[164:167], v239 offset:37888
	ds_read_b128 v[168:171], v239 offset:38912
	ds_read_b128 v[172:175], v239 offset:39936
	global_load_lds_dwordx4 v204, s[34:35]
	s_mov_b32 m0, s61
	s_nop 0
	global_load_lds_dwordx4 v208, s[34:35]
	s_waitcnt lgkmcnt(8)
	s_barrier
	s_waitcnt lgkmcnt(0)
	s_waitcnt lgkmcnt(0)
	v_mfma_f32_16x16x32_f16 v[124:127], v[128:131], v[144:147], v[124:127]
	v_mfma_f32_16x16x32_f16 v[120:123], v[136:139], v[144:147], v[120:123]
	v_mfma_f32_16x16x32_f16 v[108:111], v[128:131], v[152:155], v[108:111]
	v_mfma_f32_16x16x32_f16 v[104:107], v[136:139], v[152:155], v[104:107]
	v_mfma_f32_16x16x32_f16 v[92:95], v[128:131], v[160:163], v[92:95]
	v_mfma_f32_16x16x32_f16 v[88:91], v[136:139], v[160:163], v[88:91]
	v_mfma_f32_16x16x32_f16 v[76:79], v[128:131], v[168:171], v[76:79]
	v_mfma_f32_16x16x32_f16 v[72:75], v[136:139], v[168:171], v[72:75]
	v_mfma_f32_16x16x32_f16 v[124:127], v[132:135], v[148:151], v[124:127]
	v_mfma_f32_16x16x32_f16 v[120:123], v[140:143], v[148:151], v[120:123]
	v_mfma_f32_16x16x32_f16 v[108:111], v[132:135], v[156:159], v[108:111]
	v_mfma_f32_16x16x32_f16 v[104:107], v[140:143], v[156:159], v[104:107]
	v_mfma_f32_16x16x32_f16 v[92:95], v[132:135], v[164:167], v[92:95]
	v_mfma_f32_16x16x32_f16 v[88:91], v[140:143], v[164:167], v[88:91]
	v_mfma_f32_16x16x32_f16 v[76:79], v[132:135], v[172:175], v[76:79]
	v_mfma_f32_16x16x32_f16 v[72:75], v[140:143], v[172:175], v[72:75]
	s_barrier
	s_add_i32 s34, 0, 0x1c000
	s_add_i32 s35, s36, s31
	v_add_u32_e32 v188, s34, v238
	s_mov_b32 m0, s35
	ds_read_b128 v[176:179], v188
	ds_read_b128 v[180:183], v188 offset:1024
	ds_read_b128 v[184:187], v188 offset:2048
	ds_read_b128 v[188:191], v188 offset:3072
	global_load_lds_dwordx4 v206, s[86:87]
	s_add_i32 m0, s35, 0x2000
	s_nop 0
	global_load_lds_dwordx4 v210, s[86:87]
	s_barrier
; #define PG8_STAGE(bufoff, gbase, voff) do { _Pragma("unroll") for (int _i = 0; _i < 2; ++_i) \
;         __builtin_amdgcn_global_load_lds((const unsigned*)((const char*)(gbase) + (voff)[_i]), (LAS unsigned*)(lds + (bufoff) + ldsw + _i * 8192), 16, 0, 0); } while (0)
; #define PG8_LDA(dst, b, h) do { _Pragma("unroll") for (int m = 0; m < 4; ++m) _Pragma("unroll") for (int k = 0; k < 2; ++k) dst[m][k] = *(const LAS h16x8*)(lds + PG8_SA(b, h) + aoff + m * 2048 + k * 1024); } while (0)
; #define PG8_MMA(ai, bj, At, Bt) do { __builtin_amdgcn_s_setprio(1); _Pragma("unroll") for (int m = 0; m < 4; ++m) _Pragma("unroll") for (int n = 0; n < 2; ++n) _Pragma("unroll") for (int k = 0; k < 2; ++k) \
;         acc[ai][bj][m][n] = __builtin_amdgcn_mfma_f32_16x16x32_f16(Bt[n][k], At[m][k], acc[ai][bj][m][n], 0, 0, 0); __builtin_amdgcn_s_setprio(0); } while (0)
; #define PG8_WAIT_V(n) asm volatile("s_waitcnt vmcnt(" #n ")" ::: "memory")
; #define PG8_WAIT_L(n) asm volatile("s_waitcnt lgkmcnt(" #n ")" ::: "memory")
; #define PG8_BAR __builtin_amdgcn_s_barrier()
; #define PG8_SCHED __builtin_amdgcn_sched_barrier(0)
; __device__ __forceinline__ void gemm_phase(LAS unsigned char* lds, const Gemm g, const StaticOrder& S, const Epi& E) {
;     ...
;             PG8_LDA(At, 1, 1); PG8_STAGE(PG8_SA(1, 0), a3, voffA);
;             PG8_BAR; PG8_WAIT_L(0); PG8_MMA(1, 0, At, B0); PG8_BAR; PG8_SCHED;
;             PG8_STAGE(PG8_SB(1, 1), b3 + hstepB, voffB);
;             PG8_WAIT_V(6); PG8_BAR; PG8_MMA(1, 1, At, B1); PG8_BAR;
	s_waitcnt lgkmcnt(0)
	s_waitcnt lgkmcnt(0)
	v_mfma_f32_16x16x32_f16 v[116:119], v[176:179], v[144:147], v[116:119]
	v_mfma_f32_16x16x32_f16 v[112:115], v[184:187], v[144:147], v[112:115]
	v_mfma_f32_16x16x32_f16 v[100:103], v[176:179], v[152:155], v[100:103]
	v_mfma_f32_16x16x32_f16 v[96:99], v[184:187], v[152:155], v[96:99]
	v_mfma_f32_16x16x32_f16 v[84:87], v[176:179], v[160:163], v[84:87]
	v_mfma_f32_16x16x32_f16 v[80:83], v[184:187], v[160:163], v[80:83]
	v_mfma_f32_16x16x32_f16 v[68:71], v[176:179], v[168:171], v[68:71]
	v_mfma_f32_16x16x32_f16 v[64:67], v[184:187], v[168:171], v[64:67]
	v_mfma_f32_16x16x32_f16 v[116:119], v[180:183], v[148:151], v[116:119]
	v_mfma_f32_16x16x32_f16 v[112:115], v[188:191], v[148:151], v[112:115]
	v_mfma_f32_16x16x32_f16 v[100:103], v[180:183], v[156:159], v[100:103]
	v_mfma_f32_16x16x32_f16 v[96:99], v[188:191], v[156:159], v[96:99]
	v_mfma_f32_16x16x32_f16 v[84:87], v[180:183], v[164:167], v[84:87]
	v_mfma_f32_16x16x32_f16 v[80:83], v[188:191], v[164:167], v[80:83]
	v_mfma_f32_16x16x32_f16 v[68:71], v[180:183], v[172:175], v[68:71]
	v_mfma_f32_16x16x32_f16 v[64:67], v[188:191], v[172:175], v[64:67]
	s_mov_b32 m0, s62
	s_barrier
	ds_read_b128 v[144:147], v239 offset:49152
	ds_read_b128 v[148:151], v239 offset:50176
	ds_read_b128 v[152:155], v239 offset:51200
	ds_read_b128 v[156:159], v239 offset:52224
	ds_read_b128 v[160:163], v239 offset:53248
	ds_read_b128 v[164:167], v239 offset:54272
	ds_read_b128 v[168:171], v239 offset:55296
	ds_read_b128 v[172:175], v239 offset:56320
	global_load_lds_dwordx4 v204, s[88:89]
	s_mov_b32 m0, s63
	s_nop 0
	global_load_lds_dwordx4 v208, s[88:89]
	s_barrier
	s_waitcnt lgkmcnt(0)
	s_waitcnt lgkmcnt(0)
	v_mfma_f32_16x16x32_f16 v[60:63], v[128:131], v[144:147], v[60:63]
	v_mfma_f32_16x16x32_f16 v[56:59], v[136:139], v[144:147], v[56:59]
	v_mfma_f32_16x16x32_f16 v[44:47], v[128:131], v[152:155], v[44:47]
	v_mfma_f32_16x16x32_f16 v[40:43], v[136:139], v[152:155], v[40:43]
	v_mfma_f32_16x16x32_f16 v[28:31], v[128:131], v[160:163], v[28:31]
	v_mfma_f32_16x16x32_f16 v[24:27], v[136:139], v[160:163], v[24:27]
	v_mfma_f32_16x16x32_f16 v[12:15], v[128:131], v[168:171], v[12:15]
	v_mfma_f32_16x16x32_f16 v[8:11], v[136:139], v[168:171], v[8:11]
	v_mfma_f32_16x16x32_f16 v[60:63], v[132:135], v[148:151], v[60:63]
	v_mfma_f32_16x16x32_f16 v[56:59], v[140:143], v[148:151], v[56:59]
	v_mfma_f32_16x16x32_f16 v[44:47], v[132:135], v[156:159], v[44:47]
	v_mfma_f32_16x16x32_f16 v[40:43], v[140:143], v[156:159], v[40:43]
	v_mfma_f32_16x16x32_f16 v[28:31], v[132:135], v[164:167], v[28:31]
	v_mfma_f32_16x16x32_f16 v[24:27], v[140:143], v[164:167], v[24:27]
	v_mfma_f32_16x16x32_f16 v[12:15], v[132:135], v[172:175], v[12:15]
	v_mfma_f32_16x16x32_f16 v[8:11], v[140:143], v[172:175], v[8:11]
	s_barrier
	s_add_i32 s34, s34, s31
	s_mov_b32 m0, s34
	s_nop 0
	global_load_lds_dwordx4 v206, s[96:97]
	s_add_i32 m0, s34, 0x2000
	s_nop 0
	global_load_lds_dwordx4 v210, s[96:97]
	s_waitcnt vmcnt(6)
	s_barrier
	v_mfma_f32_16x16x32_f16 v[52:55], v[176:179], v[144:147], v[52:55]
	v_mfma_f32_16x16x32_f16 v[48:51], v[184:187], v[144:147], v[48:51]
	v_mfma_f32_16x16x32_f16 v[36:39], v[176:179], v[152:155], v[36:39]
	v_mfma_f32_16x16x32_f16 v[32:35], v[184:187], v[152:155], v[32:35]
	v_mfma_f32_16x16x32_f16 v[20:23], v[176:179], v[160:163], v[20:23]
	v_mfma_f32_16x16x32_f16 v[16:19], v[184:187], v[160:163], v[16:19]
	v_mfma_f32_16x16x32_f16 v[4:7], v[176:179], v[168:171], v[4:7]
	v_mfma_f32_16x16x32_f16 v[0:3], v[184:187], v[168:171], v[0:3]
	v_mfma_f32_16x16x32_f16 v[52:55], v[180:183], v[148:151], v[52:55]
	v_mfma_f32_16x16x32_f16 v[48:51], v[188:191], v[148:151], v[48:51]
	v_mfma_f32_16x16x32_f16 v[36:39], v[180:183], v[156:159], v[36:39]
	v_mfma_f32_16x16x32_f16 v[32:35], v[188:191], v[156:159], v[32:35]
	v_mfma_f32_16x16x32_f16 v[20:23], v[180:183], v[164:167], v[20:23]
	v_mfma_f32_16x16x32_f16 v[16:19], v[188:191], v[164:167], v[16:19]
	v_mfma_f32_16x16x32_f16 v[4:7], v[180:183], v[172:175], v[4:7]
	v_mfma_f32_16x16x32_f16 v[0:3], v[188:191], v[172:175], v[0:3]
	s_add_u32 s0, s0, 0x100
	s_addc_u32 s1, s1, 0
	s_add_u32 s27, s27, 0x100
	s_addc_u32 s33, s33, 0
	s_cmp_ge_u32 s38, s64
	s_mov_b32 s34, s38
	s_barrier
	s_cbranch_scc0 .LBB0_762
	s_setprio 0
	s_lshl_b32 s0, s84, 8
	s_or_b32 s27, s0, s65
	v_lshl_add_u32 v240, s30, 8, v200
	v_or_b32_e32 v216, s27, v202
	s_cmp_eq_u32 s93, 3
	s_cbranch_scc1 .Lst16_fast
	s_cmp_eq_u32 s93, 1
	s_cbranch_scc0 .Llora_no
	s_lshr_b32 s0, s84, 2
	s_cmp_lt_u32 s0, 2
	s_cbranch_scc1 .Llora_fast
